# combo17: combo16 + rope-table loop reads its positions from a wave-private LDS stage filled by 8 loads issued together (no per-iteration global load + full wait)
# baseline (speedup 1.0000x reference)
; __global__ void __launch_bounds__(512, 2) mega_fwd(Args a) {
;     ...
;     { const int gt = blockIdx.x * 512 + tid, GT = G * 512;
;       for (int e = gt; e < T * 32; e += GT) { const int t = e >> 5, j = e & 31;
;           const float ang = (float)pos[t] * a.inv_freq[j];
;           const double turns = (double)ang * 0.15915494309189535; const float fr = (float)(turns - rint(turns)) * 6.283185307179586f;
;           cosT[e] = cosf(fr); sinT[e] = sinf(fr); } }
.LBB0_20:
	s_lshl_b32 s2, s66, 9
	v_writelane_b32 v252, s2, 5
	v_add_u32_e32 v2, s2, v1
	s_mov_b32 s2, 0x100000
	v_cmp_gt_i32_e32 vcc, s2, v2
	s_barrier
	s_and_saveexec_b64 s[14:15], vcc
	s_cbranch_execz .LBB0_31
	v_and_b32_e32 v3, 31, v1
	v_lshlrev_b32_e32 v3, 2, v3
	global_load_dword v8, v3, s[0:1] offset:176
	v_ashrrev_i32_e32 v3, 31, v2
	v_lshl_add_u64 v[4:5], v[2:3], 2, s[90:91]
	s_mov_b64 s[2:3], 0x2f00000
	s_mov_b32 s18, 0x6dc9c883
	v_lshl_add_u64 v[4:5], v[4:5], 0, s[2:3]
	s_mov_b64 s[16:17], 0
	s_mov_b32 s19, 0x3fc45f30
	s_brev_b32 s25, 18
	s_mov_b32 s26, 0xfe5163ab
	v_mov_b32_e32 v7, 0
	s_mov_b32 s27, 0x3c439041
	s_mov_b32 s28, 0xdb629599
	s_mov_b32 s29, 0xf534ddc0
	s_mov_b32 s30, 0xfc2757d1
	s_mov_b32 s31, 0x4e441529
	s_mov_b32 s34, 0xa2f9836e
	s_mov_b32 s35, 0x3fc90fda
	s_mov_b32 s36, 0x3f22f983
	s_mov_b32 s37, 0xbfc90fda
	v_mov_b32_e32 v3, 0x3c0881c4
	v_mov_b32_e32 v9, 0xbab64f3b
	s_brev_b32 s38, 1
	s_movk_i32 s39, 0x1f8
	s_mov_b64 s[20:21], 0x80000
	s_mov_b32 s40, 0xdffff
	v_not_b32_e32 v10, 63
	v_not_b32_e32 v11, 31
	v_mov_b32_e32 v12, 0x7fc00000
	v_mov_b32_e32 v13, v2
	v_ashrrev_i32_e32 v14, 5, v2
	v_ashrrev_i32_e32 v15, 31, v14
	v_lshl_add_u64 v[14:15], v[14:15], 2, s[72:73]
	s_mov_b64 s[2:3], 0x4000
	global_load_dword v16, v[14:15], off
	v_lshl_add_u64 v[14:15], v[14:15], 0, s[2:3]
	global_load_dword v17, v[14:15], off
	v_lshl_add_u64 v[14:15], v[14:15], 0, s[2:3]
	global_load_dword v18, v[14:15], off
	v_lshl_add_u64 v[14:15], v[14:15], 0, s[2:3]
	global_load_dword v19, v[14:15], off
	v_lshl_add_u64 v[14:15], v[14:15], 0, s[2:3]
	global_load_dword v20, v[14:15], off
	v_lshl_add_u64 v[14:15], v[14:15], 0, s[2:3]
	global_load_dword v21, v[14:15], off
	v_lshl_add_u64 v[14:15], v[14:15], 0, s[2:3]
	global_load_dword v22, v[14:15], off
	v_lshl_add_u64 v[14:15], v[14:15], 0, s[2:3]
	global_load_dword v23, v[14:15], off
	v_lshrrev_b32_e32 v33, 6, v190
	v_lshlrev_b32_e32 v33, 14, v33
	v_and_b32_e32 v14, 63, v190
	v_lshl_or_b32 v33, v14, 2, v33
	s_waitcnt vmcnt(0)
	ds_write_b32 v33, v16 offset:0
	ds_write_b32 v33, v17 offset:256
	ds_write_b32 v33, v18 offset:512
	ds_write_b32 v33, v19 offset:768
	ds_write_b32 v33, v20 offset:1024
	ds_write_b32 v33, v21 offset:1280
	ds_write_b32 v33, v22 offset:1536
	ds_write_b32 v33, v23 offset:1792
	s_waitcnt lgkmcnt(0)
	s_branch .LBB0_23

; __global__ void __launch_bounds__(512, 2) mega_fwd(Args a) {
;     ...
;       for (int e = gt; e < T * 32; e += GT) { const int t = e >> 5, j = e & 31;
;           const float ang = (float)pos[t] * a.inv_freq[j];
;           const double turns = (double)ang * 0.15915494309189535; const float fr = (float)(turns - rint(turns)) * 6.283185307179586f;
;           cosT[e] = cosf(fr); sinT[e] = sinf(fr); } }
.LBB0_23:
	v_lshrrev_b32_e32 v14, 17, v13
	v_lshl_add_u32 v14, v14, 8, v33
	ds_read_b32 v6, v14
	s_waitcnt lgkmcnt(0)
	v_cvt_f32_i32_e32 v6, v6
	v_mul_f32_e32 v6, v8, v6
	v_cvt_f64_f32_e32 v[14:15], v6
	v_mul_f64 v[16:17], v[14:15], s[18:19]
	v_rndne_f64_e32 v[16:17], v[16:17]
	v_fma_f64 v[14:15], v[14:15], s[18:19], -v[16:17]
	v_cvt_f32_f64_e32 v6, v[14:15]
	v_mul_f32_e32 v14, 0x40c90fdb, v6
	v_and_b32_e32 v15, 0x7fffffff, v14
	v_lshrrev_b32_e32 v6, 23, v15
	v_and_b32_e32 v16, 0x7fffff, v15
	v_cmp_nlt_f32_e64 s[8:9], |v14|, s25
	v_add_u32_e32 v17, 0xffffff88, v6
	v_or_b32_e32 v16, 0x800000, v16
	s_and_saveexec_b64 s[2:3], s[8:9]
	s_xor_b64 s[22:23], exec, s[2:3]
	s_cbranch_execz .LBB0_25
	v_cmp_lt_u32_e32 vcc, 63, v17
	s_nop 1
	v_cndmask_b32_e32 v6, 0, v10, vcc
	v_add_u32_e32 v6, v6, v17
	v_cmp_lt_u32_e64 s[2:3], 31, v6
	s_nop 1
	v_cndmask_b32_e64 v18, 0, v11, s[2:3]
	v_add_u32_e32 v6, v18, v6
	v_cmp_lt_u32_e64 s[4:5], 31, v6
	s_nop 1
	v_cndmask_b32_e64 v18, 0, v11, s[4:5]
	v_add_u32_e32 v32, v18, v6
	v_mad_u64_u32 v[18:19], s[6:7], v16, s26, 0
	v_mov_b32_e32 v6, v19
	v_mad_u64_u32 v[20:21], s[6:7], v16, s27, v[6:7]
	v_mov_b32_e32 v6, v21
	v_mad_u64_u32 v[22:23], s[6:7], v16, s28, v[6:7]
	v_mov_b32_e32 v6, v23
	v_mad_u64_u32 v[24:25], s[6:7], v16, s29, v[6:7]
	v_mov_b32_e32 v6, v25
	v_mad_u64_u32 v[26:27], s[6:7], v16, s30, v[6:7]
	v_mov_b32_e32 v6, v27
	v_mad_u64_u32 v[28:29], s[6:7], v16, s31, v[6:7]
	v_mov_b32_e32 v6, v29
	v_mad_u64_u32 v[30:31], s[6:7], v16, s34, v[6:7]
	v_cndmask_b32_e32 v19, v28, v24, vcc
	v_cndmask_b32_e32 v6, v30, v26, vcc
	v_cndmask_b32_e32 v23, v31, v28, vcc
	v_cndmask_b32_e64 v21, v6, v19, s[2:3]
	v_cndmask_b32_e64 v6, v23, v6, s[2:3]
	v_cndmask_b32_e32 v23, v26, v22, vcc
	v_cndmask_b32_e64 v19, v19, v23, s[2:3]
	v_cndmask_b32_e32 v20, v24, v20, vcc
	v_cndmask_b32_e64 v6, v6, v21, s[4:5]
	v_cndmask_b32_e64 v21, v21, v19, s[4:5]
	v_sub_u32_e32 v25, 32, v32
	v_cndmask_b32_e64 v23, v23, v20, s[2:3]
	v_alignbit_b32 v26, v6, v21, v25
	v_cmp_eq_u32_e64 s[6:7], 0, v32
	v_cndmask_b32_e64 v19, v19, v23, s[4:5]
	v_cndmask_b32_e32 v18, v22, v18, vcc
	v_cndmask_b32_e64 v6, v26, v6, s[6:7]
	v_alignbit_b32 v24, v21, v19, v25
	v_cndmask_b32_e64 v18, v20, v18, s[2:3]
	v_cndmask_b32_e64 v21, v24, v21, s[6:7]
	v_bfe_u32 v27, v6, 29, 1
	v_cndmask_b32_e64 v18, v23, v18, s[4:5]
	v_alignbit_b32 v24, v6, v21, 30
	v_sub_u32_e32 v28, 0, v27
	v_alignbit_b32 v20, v19, v18, v25
	v_xor_b32_e32 v24, v24, v28
	v_cndmask_b32_e64 v19, v20, v19, s[6:7]
	v_alignbit_b32 v20, v21, v19, 30
	v_ffbh_u32_e32 v21, v24
	v_min_u32_e32 v21, 32, v21
	v_alignbit_b32 v18, v19, v18, 30
	v_xor_b32_e32 v20, v20, v28
	v_sub_u32_e32 v22, 31, v21
	v_xor_b32_e32 v18, v18, v28
	v_alignbit_b32 v23, v24, v20, v22
	v_alignbit_b32 v18, v20, v18, v22
	v_alignbit_b32 v19, v23, v18, 9
	v_ffbh_u32_e32 v20, v19
	v_min_u32_e32 v20, 32, v20
	v_lshrrev_b32_e32 v26, 29, v6
	v_not_b32_e32 v22, v20
	v_alignbit_b32 v18, v19, v18, v22
	v_lshlrev_b32_e32 v19, 31, v26
	v_or_b32_e32 v22, 0x33000000, v19
	v_add_lshl_u32 v20, v20, v21, 23
	v_lshrrev_b32_e32 v18, 9, v18
	v_sub_u32_e32 v20, v22, v20
	v_or_b32_e32 v19, 0.5, v19
	v_lshlrev_b32_e32 v21, 23, v21
	v_or_b32_e32 v18, v20, v18
	v_lshrrev_b32_e32 v20, 9, v23
	v_sub_u32_e32 v19, v19, v21
	v_or_b32_e32 v19, v20, v19
	v_mul_f32_e32 v20, 0x3fc90fda, v19
	v_fma_f32 v21, v19, s35, -v20
	v_fmac_f32_e32 v21, 0x33a22168, v19
	v_fmac_f32_e32 v21, 0x3fc90fda, v18
	v_lshrrev_b32_e32 v6, 30, v6
	v_add_f32_e32 v19, v20, v21
	v_add_u32_e32 v18, v27, v6
